# FoX fast path: decay subtract fused into the score FMA (v_fma with SGPR scale, negated cum operand)
# speedup vs baseline: 1.0217x; 1.0056x over previous
; DEVI int opaque_tid() { int t = __builtin_amdgcn_workitem_id_x(); asm volatile("" : "+v"(t)); return t; }
; DEVI char* opaque_ptr(char* p) { asm volatile("" : "+s"(p)); return p; }
; #define LAS __attribute__((address_space(3)))
; __global__ void __launch_bounds__(256, 2) mega(Params p) {
;   __shared__ __attribute__((aligned(16))) char smem[SMEM_BYTES];
;   cg::grid_group grid = cg::this_grid();
;   char* ws = opaque_ptr(p.ws);
;   volatile LAS unsigned* xst = (volatile LAS unsigned*)(smem + XBST);
;   if (opaque_tid() < 4) xst[opaque_tid()] = 0u;
;   __syncthreads();
_Z4mega6Params:
	s_mov_b32 s101, 0x3e38aa3b
	s_load_dwordx4 s[88:91], s[0:1], 0xc0
	s_load_dword s11, s[0:1], 0xd8
	s_load_dwordx2 s[20:21], s[0:1], 0xd0
	v_and_b32_e32 v154, 0x3ff, v0
	s_add_u32 s96, s0, 0xd0
	v_mov_b32_e32 v1, v154
	s_waitcnt lgkmcnt(0)
	s_mov_b64 s[22:23], s[90:91]
	s_addc_u32 s97, s1, 0
	s_nop 0
	v_cmp_gt_i32_e32 vcc, 4, v1
	s_and_saveexec_b64 s[6:7], vcc
	s_cbranch_execz .LBB0_2
	v_mov_b32_e32 v1, v154
	v_mov_b32_e32 v2, 0x12da0
	v_lshl_add_u32 v1, v1, 2, v2
	v_mov_b32_e32 v2, 0
	ds_write_b32 v1, v2

; DEVI float opq(float x) { asm("" : "+v"(x)); return x; }
; template <int DK, int MODE, int RBM, class SF, class FF, class POST>
; DEVI void attn_tile_body(const bf16x8 (&qf)[2][DK / 32], const char* Ks, const char* Vs, SF& sf, FF& ff, POST& post,
;                          int cur, int c0, int c1, float (&m)[2], float (&l)[2], f32x4 (&o)[5][2], int fr, int fq) {
;     ...
;   for (int ks = 0; ks < NKC; ++ks)
; #pragma unroll
;     for (int kb = 0; kb < 4; ++kb) {
;       const int koff = DK == 64 ? (kb * 16 + fr) * 128 + (((ks * 4 + fq) ^ (fr & 7)) * 16)
;                                 : (kb * 16 + fr) * 192 + ((ks * 4 + (fq ^ ((fr >> 2) & 3))) * 16);
;       bf16x8 kf = *(const bf16x8*)(Ks + koff);
;       if (RBM & 1) s[kb][0] = __builtin_amdgcn_mfma_f32_16x16x32_bf16(kf, qf[0][ks], s[kb][0], 0, 0, 0);
;       if (RBM & 2) s[kb][1] = __builtin_amdgcn_mfma_f32_16x16x32_bf16(kf, qf[1][ks], s[kb][1], 0, 0, 0);
;     }
; #pragma unroll
;   for (int rb = 0; rb < 2; ++rb) {
;     if (!(RBM & (1 << rb))) continue;
;     const int cm = rb == 0 ? c0 : c1;
;     if (cm == 2) {
;       const float cl = ff.cl(rb, cur);
;       const float fsc = ff.sc;
;       if (FF::HASVEC) {
; #pragma unroll
;         for (int kb = 0; kb < 4; ++kb) {
;           const f32x4 av = ff.vec(kb);
; #pragma unroll
;           for (int j = 0; j < 4; ++j) s[kb][rb][j] = opq(fmaf(s[kb][rb][j], fsc, av[j]));
;         }
;       }
; template <int KIND>
; DEVI void mha_item(const Params& p, int b, int h, int t0, char* smem) {
;     ...
;   auto clm = [&](int rb, int tile) { return (KIND == 2 || tile * 64 + 63 <= t0 + uw * 32 + rb * 16) ? 2 : 1; };
.LBB0_539:
	s_or_b64 exec, exec, s[54:55]
	v_lshrrev_b64 v[2:3], v60, v[118:119]
	s_and_b64 s[6:7], exec, vcc
	v_and_b32_e32 v2, 1, v2
	s_or_b64 s[52:53], s[6:7], s[52:53]
	v_cmp_eq_u32_e32 vcc, 1, v2
	s_and_saveexec_b64 s[38:39], vcc
	s_cbranch_execz .LBB0_557
	v_lshlrev_b32_e32 v197, 6, v60
	s_mul_i32 s6, s42, 0x4100
	v_or_b32_e32 v2, 63, v197
	v_cmp_le_i32_e32 vcc, v2, v113
	v_add_u32_e32 v2, s6, v115
	v_add_u32_e32 v3, v2, v123
	ds_read_b128 v[72:75], v3 offset:4096
	ds_read_b128 v[60:63], v3
	v_add_u32_e32 v2, v2, v134
	ds_read_b128 v[68:71], v3 offset:2048
	s_waitcnt lgkmcnt(0)
	v_mfma_f32_16x16x32_bf16 v[80:83], v[72:75], v[8:11], 0
	v_mfma_f32_16x16x32_bf16 v[144:147], v[72:75], v[16:19], 0
	ds_read_b128 v[72:75], v3 offset:6144
	s_waitcnt lgkmcnt(0)
	v_mfma_f32_16x16x32_bf16 v[148:151], v[72:75], v[8:11], 0
	v_mfma_f32_16x16x32_bf16 v[192:195], v[72:75], v[16:19], 0
	ds_read_b128 v[72:75], v2
	v_mfma_f32_16x16x32_bf16 v[64:67], v[60:63], v[8:11], 0
	v_mfma_f32_16x16x32_bf16 v[60:63], v[60:63], v[16:19], 0
	s_waitcnt lgkmcnt(0)
	v_mfma_f32_16x16x32_bf16 v[92:95], v[72:75], v[4:7], v[64:67]
	v_mfma_f32_16x16x32_bf16 v[72:75], v[72:75], v[12:15], v[60:63]
	s_nop 4
	ds_read_b128 v[60:63], v2 offset:2048
	v_mfma_f32_16x16x32_bf16 v[76:79], v[68:71], v[8:11], 0
	v_mfma_f32_16x16x32_bf16 v[68:71], v[68:71], v[16:19], 0
	s_waitcnt lgkmcnt(0)
	v_mfma_f32_16x16x32_bf16 v[88:91], v[60:63], v[4:7], v[76:79]
	v_mfma_f32_16x16x32_bf16 v[68:71], v[60:63], v[12:15], v[68:71]
	ds_read_b128 v[60:63], v2 offset:4096
	s_waitcnt lgkmcnt(0)
	v_mfma_f32_16x16x32_bf16 v[84:87], v[60:63], v[4:7], v[80:83]
	v_mfma_f32_16x16x32_bf16 v[64:67], v[60:63], v[12:15], v[144:147]
	ds_read_b128 v[60:63], v2 offset:6144
	s_waitcnt lgkmcnt(0)
	v_mfma_f32_16x16x32_bf16 v[80:83], v[60:63], v[4:7], v[148:151]
	v_add_u32_e32 v144, s6, v106
	v_mfma_f32_16x16x32_bf16 v[60:63], v[60:63], v[12:15], v[192:195]
	s_and_saveexec_b64 s[54:55], vcc
	s_xor_b64 s[54:55], exec, s[54:55]
	s_cbranch_execz .LBB0_544
	ds_read_b128 v[76:79], v144 offset:16384
	ds_read_b128 v[148:151], v144 offset:16576
	s_waitcnt lgkmcnt(0)
	v_fma_f32 v146, v92, s101, -v76
	v_fma_f32 v145, v93, s101, -v77
	v_fma_f32 v93, v94, s101, -v78
	v_fma_f32 v92, v95, s101, -v79
	ds_read_b128 v[76:79], v144 offset:16448
	s_waitcnt lgkmcnt(0)
	v_fma_f32 v94, v88, s101, -v76
	v_fma_f32 v88, v89, s101, -v77
	v_fma_f32 v89, v90, s101, -v78
	v_fma_f32 v90, v91, s101, -v79
	s_waitcnt vmcnt(0)
	ds_read_b128 v[76:79], v144 offset:16512
	v_max_f32_e32 v2, v145, v145
	v_max_f32_e32 v3, v146, v146
	s_waitcnt lgkmcnt(0)
	v_fma_f32 v91, v85, s101, -v77
	v_fma_f32 v85, v86, s101, -v78
	v_fma_f32 v86, v80, s101, -v148
	v_fma_f32 v95, v84, s101, -v76
	v_fma_f32 v80, v81, s101, -v149
	v_fma_f32 v84, v87, s101, -v79
	v_fma_f32 v81, v82, s101, -v150
	v_fma_f32 v82, v83, s101, -v151
	v_max_f32_e32 v2, v3, v2
	v_max3_f32 v3, v92, v94, v88
	v_max3_f32 v83, v91, v85, v84
	v_max3_f32 v87, v86, v80, v81
	s_nop 0
	v_max3_f32 v76, v89, v90, v95
	v_max3_f32 v2, v2, v93, v3
	v_max3_f32 v3, v83, v87, v82
	v_max3_f32 v2, v2, v76, v3
	v_mov_b32_e32 v3, v2
	s_nop 1
	v_permlane16_swap_b32_e32 v2, v3
	v_max_f32_e32 v2, v2, v3
	v_mov_b32_e32 v3, v2
	s_nop 1
	v_permlane32_swap_b32_e32 v2, v3
	v_max_f32_e32 v124, v2, v3
	v_pk_add_f32 v[2:3], v[108:109], v[124:125]
	s_nop 0
	v_cmp_gt_f32_e32 vcc, v2, v3
	s_cbranch_vccz .LBB0_543
	v_max_f32_e32 v3, v109, v109
	v_max_f32_e32 v2, v3, v2
	v_sub_f32_e32 v3, v109, v2
	v_exp_f32_e32 v3, v3
	v_mov_b32_e32 v109, v2
	v_mul_f32_e32 v56, v56, v3
	v_mul_f32_e32 v57, v57, v3
	v_mul_f32_e32 v58, v58, v3
	v_mul_f32_e32 v59, v59, v3
	v_mul_f32_e32 v52, v52, v3
	v_mul_f32_e32 v53, v53, v3
	v_mul_f32_e32 v54, v54, v3
	v_mul_f32_e32 v55, v55, v3
	v_mul_f32_e32 v48, v48, v3
	v_mul_f32_e32 v49, v49, v3
	v_mul_f32_e32 v50, v50, v3
	v_mul_f32_e32 v51, v51, v3
	v_mul_f32_e32 v44, v44, v3
	v_mul_f32_e32 v45, v45, v3
	v_mul_f32_e32 v46, v46, v3
	v_mul_f32_e32 v47, v47, v3
	v_mul_f32_e32 v24, v24, v3
	v_mul_f32_e32 v25, v25, v3
	v_mul_f32_e32 v26, v26, v3
	v_mul_f32_e32 v27, v27, v3

; DEVI float opq(float x) { asm("" : "+v"(x)); return x; }
; DEVI float fexp2(float x) { return __builtin_amdgcn_exp2f(x); }
; template <int DK, int MODE, int RBM, class SF, class FF, class POST>
; DEVI void attn_tile_body(const bf16x8 (&qf)[2][DK / 32], const char* Ks, const char* Vs, SF& sf, FF& ff, POST& post,
;                          int cur, int c0, int c1, float (&m)[2], float (&l)[2], f32x4 (&o)[5][2], int fr, int fq) {
;     ...
;     if (cm == 2) {
;       const float cl = ff.cl(rb, cur);
;       const float fsc = ff.sc;
;       if (FF::HASVEC) {
; #pragma unroll
;         for (int kb = 0; kb < 4; ++kb) {
;           const f32x4 av = ff.vec(kb);
; #pragma unroll
;           for (int j = 0; j < 4; ++j) s[kb][rb][j] = opq(fmaf(s[kb][rb][j], fsc, av[j]));
;         }
;       }
;       if (MODE == 2) {
;         const float c = cl - m[rb];
; #pragma unroll
;         for (int kb = 0; kb < 4; ++kb)
; #pragma unroll
;           for (int j = 0; j < 4; ++j) {
;             const float e = FF::HASVEC ? opq(s[kb][rb][j] + c) : opq(fmaf(s[kb][rb][j], fsc, c));
;             s[kb][rb][j] = opq(fexp2(e) * l[rb]);
;           }
;       } else if (MODE == 0) {
;         float mx = max16(s[0][rb], s[1][rb], s[2][rb], s[3][rb]);
;         mx = xmax16(mx); mx = xmax32(mx);
;         const float cand = FF::HASVEC ? (mx + cl) : fmaf(mx, fsc, cl);
;         if (__builtin_amdgcn_ballot_w64(cand > m[rb] + DEFER_THR) != 0) {
;           const float mn = fmaxf(m[rb], cand);
;           const float alpha = fexp2(m[rb] - mn);
;           m[rb] = mn;
; #pragma unroll
;           for (int db = 0; db < 5; ++db)
; #pragma unroll
;             for (int j = 0; j < 4; ++j) o[db][rb][j] = opq(o[db][rb][j] * alpha);
;         }
; template <int KIND>
; DEVI void mha_item(const Params& p, int b, int h, int t0, char* smem) {
;     ...
;   auto clm = [&](int rb, int tile) { return (KIND == 2 || tile * 64 + 63 <= t0 + uw * 32 + rb * 16) ? 2 : 1; };
.LBB0_548:
	s_or_b64 exec, exec, s[54:55]
	v_or_b32_e32 v80, 47, v197
	v_cmp_le_i32_e32 vcc, v80, v113
	s_and_saveexec_b64 s[54:55], vcc
	s_xor_b64 s[54:55], exec, s[54:55]
	s_cbranch_execz .LBB0_552
	ds_read_b128 v[78:81], v144 offset:16384
	s_waitcnt lgkmcnt(0)
	v_fma_f32 v78, v72, s101, -v78
	v_fma_f32 v77, v73, s101, -v79
	v_fma_f32 v73, v74, s101, -v80
	v_fma_f32 v72, v75, s101, -v81
	ds_read_b128 v[80:83], v144 offset:16448
	s_waitcnt lgkmcnt(0)
	v_fma_f32 v74, v68, s101, -v80
	v_fma_f32 v68, v69, s101, -v81
	v_fma_f32 v69, v70, s101, -v82
	v_fma_f32 v70, v71, s101, -v83
	ds_read_b128 v[80:83], v144 offset:16512
	v_max_f32_e32 v2, v77, v77
	v_max_f32_e32 v3, v78, v78
	s_waitcnt lgkmcnt(0)
	v_fma_f32 v75, v64, s101, -v80
	v_fma_f32 v71, v65, s101, -v81
	v_fma_f32 v65, v66, s101, -v82
	v_fma_f32 v64, v67, s101, -v83
	ds_read_b128 v[80:83], v144 offset:16576
	s_waitcnt lgkmcnt(0)
	v_fma_f32 v66, v60, s101, -v80
	v_fma_f32 v60, v61, s101, -v81
	v_fma_f32 v61, v62, s101, -v82
	v_fma_f32 v62, v63, s101, -v83
	v_max_f32_e32 v2, v3, v2
	v_max3_f32 v3, v72, v74, v68
	v_max3_f32 v67, v71, v65, v64
	v_max3_f32 v79, v66, v60, v61
	s_nop 0
	v_max3_f32 v63, v69, v70, v75
	v_max3_f32 v2, v2, v73, v3
	v_max3_f32 v3, v67, v79, v62
	v_max3_f32 v2, v2, v63, v3
	v_mov_b32_e32 v3, v2
	s_nop 1
	v_permlane16_swap_b32_e32 v2, v3
	v_max_f32_e32 v2, v2, v3
	v_mov_b32_e32 v3, v2
	s_nop 1
	v_permlane32_swap_b32_e32 v2, v3
	v_max_f32_e32 v124, v2, v3
	v_pk_add_f32 v[2:3], v[110:111], v[124:125]
	s_nop 0
	v_cmp_gt_f32_e32 vcc, v2, v3
	s_cbranch_vccz .LBB0_551
	v_max_f32_e32 v3, v111, v111
	v_max_f32_e32 v2, v3, v2
	v_sub_f32_e32 v3, v111, v2
	v_exp_f32_e32 v3, v3
	v_mov_b32_e32 v111, v2
	v_mul_f32_e32 v40, v40, v3
	v_mul_f32_e32 v41, v41, v3
	v_mul_f32_e32 v42, v42, v3
	v_mul_f32_e32 v43, v43, v3
	v_mul_f32_e32 v36, v36, v3
	v_mul_f32_e32 v37, v37, v3
	v_mul_f32_e32 v38, v38, v3
	v_mul_f32_e32 v39, v39, v3
	v_mul_f32_e32 v32, v32, v3
	v_mul_f32_e32 v33, v33, v3
	v_mul_f32_e32 v34, v34, v3
	v_mul_f32_e32 v35, v35, v3
	v_mul_f32_e32 v28, v28, v3
	v_mul_f32_e32 v29, v29, v3
	v_mul_f32_e32 v30, v30, v3
	v_mul_f32_e32 v31, v31, v3
	v_mul_f32_e32 v20, v20, v3
	v_mul_f32_e32 v21, v21, v3
	v_mul_f32_e32 v22, v22, v3
	v_mul_f32_e32 v23, v23, v3

; DEVI float opq(float x) { asm("" : "+v"(x)); return x; }
; template <int DK, int MODE, int RBM, class SF, class FF, class POST>
; DEVI void attn_tile_body(const bf16x8 (&qf)[2][DK / 32], const char* Ks, const char* Vs, SF& sf, FF& ff, POST& post,
;                          int cur, int c0, int c1, float (&m)[2], float (&l)[2], f32x4 (&o)[5][2], int fr, int fq) {
;     ...
;   for (int ks = 0; ks < NKC; ++ks)
; #pragma unroll
;     for (int kb = 0; kb < 4; ++kb) {
;       const int koff = DK == 64 ? (kb * 16 + fr) * 128 + (((ks * 4 + fq) ^ (fr & 7)) * 16)
;                                 : (kb * 16 + fr) * 192 + ((ks * 4 + (fq ^ ((fr >> 2) & 3))) * 16);
;       bf16x8 kf = *(const bf16x8*)(Ks + koff);
;       if (RBM & 1) s[kb][0] = __builtin_amdgcn_mfma_f32_16x16x32_bf16(kf, qf[0][ks], s[kb][0], 0, 0, 0);
;       if (RBM & 2) s[kb][1] = __builtin_amdgcn_mfma_f32_16x16x32_bf16(kf, qf[1][ks], s[kb][1], 0, 0, 0);
;     }
; #pragma unroll
;   for (int rb = 0; rb < 2; ++rb) {
;     if (!(RBM & (1 << rb))) continue;
;     const int cm = rb == 0 ? c0 : c1;
;     if (cm == 2) {
;       const float cl = ff.cl(rb, cur);
;       const float fsc = ff.sc;
;       if (FF::HASVEC) {
; #pragma unroll
;         for (int kb = 0; kb < 4; ++kb) {
;           const f32x4 av = ff.vec(kb);
; #pragma unroll
;           for (int j = 0; j < 4; ++j) s[kb][rb][j] = opq(fmaf(s[kb][rb][j], fsc, av[j]));
;         }
;       }
.LBB0_557:
	s_or_b64 exec, exec, s[38:39]
	v_cmp_lt_i32_e32 vcc, -1, v143
	s_and_saveexec_b64 s[38:39], vcc
	s_cbranch_execz .LBB0_530
	v_lshrrev_b64 v[2:3], v143, v[118:119]
	v_and_b32_e32 v2, 1, v2
	v_cmp_eq_u32_e32 vcc, 1, v2
	s_and_saveexec_b64 s[54:55], vcc
	s_cbranch_execz .LBB0_529
	v_lshlrev_b32_e32 v196, 6, v143
	s_mul_i32 s6, s42, 0x4100
	v_or_b32_e32 v2, 63, v196
	v_cmp_le_i32_e32 vcc, v2, v113
	v_add_u32_e32 v2, s6, v115
	v_add_u32_e32 v3, v2, v123
	ds_read_b128 v[72:75], v3 offset:20736
	ds_read_b128 v[60:63], v3 offset:16640
	v_add_u32_e32 v2, v2, v134
	ds_read_b128 v[68:71], v3 offset:18688
	v_add_u32_e32 v143, s6, v106
	s_waitcnt lgkmcnt(0)
	v_mfma_f32_16x16x32_bf16 v[80:83], v[72:75], v[8:11], 0
	v_mfma_f32_16x16x32_bf16 v[144:147], v[72:75], v[16:19], 0
	ds_read_b128 v[72:75], v3 offset:22784
	s_waitcnt lgkmcnt(0)
	v_mfma_f32_16x16x32_bf16 v[148:151], v[72:75], v[8:11], 0
	v_mfma_f32_16x16x32_bf16 v[192:195], v[72:75], v[16:19], 0
	ds_read_b128 v[72:75], v2 offset:16640
	v_mfma_f32_16x16x32_bf16 v[64:67], v[60:63], v[8:11], 0
	v_mfma_f32_16x16x32_bf16 v[60:63], v[60:63], v[16:19], 0
	s_waitcnt lgkmcnt(0)
	v_mfma_f32_16x16x32_bf16 v[92:95], v[72:75], v[4:7], v[64:67]
	v_mfma_f32_16x16x32_bf16 v[72:75], v[72:75], v[12:15], v[60:63]
	s_nop 4
	ds_read_b128 v[60:63], v2 offset:18688
	v_mfma_f32_16x16x32_bf16 v[76:79], v[68:71], v[8:11], 0
	v_mfma_f32_16x16x32_bf16 v[68:71], v[68:71], v[16:19], 0
	s_waitcnt lgkmcnt(0)
	v_mfma_f32_16x16x32_bf16 v[88:91], v[60:63], v[4:7], v[76:79]
	v_mfma_f32_16x16x32_bf16 v[68:71], v[60:63], v[12:15], v[68:71]
	ds_read_b128 v[60:63], v2 offset:20736
	s_waitcnt lgkmcnt(0)
	v_mfma_f32_16x16x32_bf16 v[84:87], v[60:63], v[4:7], v[80:83]
	v_mfma_f32_16x16x32_bf16 v[64:67], v[60:63], v[12:15], v[144:147]
	ds_read_b128 v[60:63], v2 offset:22784
	s_waitcnt lgkmcnt(0)
	v_mfma_f32_16x16x32_bf16 v[80:83], v[60:63], v[4:7], v[148:151]
	v_mfma_f32_16x16x32_bf16 v[60:63], v[60:63], v[12:15], v[192:195]
	s_and_saveexec_b64 s[82:83], vcc
	s_xor_b64 s[94:95], exec, s[82:83]
	s_cbranch_execz .LBB0_563
	ds_read_b128 v[76:79], v143 offset:33024
	ds_read_b128 v[146:149], v143 offset:33216
	s_waitcnt lgkmcnt(0)
	v_fma_f32 v145, v92, s101, -v76
	v_fma_f32 v144, v93, s101, -v77
	v_fma_f32 v93, v94, s101, -v78
	v_fma_f32 v92, v95, s101, -v79
	ds_read_b128 v[76:79], v143 offset:33088
	s_waitcnt lgkmcnt(0)
	v_fma_f32 v94, v88, s101, -v76
	v_fma_f32 v88, v89, s101, -v77
	v_fma_f32 v89, v90, s101, -v78
	v_fma_f32 v90, v91, s101, -v79
	s_waitcnt vmcnt(0)
	ds_read_b128 v[76:79], v143 offset:33152
	v_max_f32_e32 v2, v144, v144
	v_max_f32_e32 v3, v145, v145
	s_waitcnt lgkmcnt(0)
	v_fma_f32 v91, v85, s101, -v77
	v_fma_f32 v85, v86, s101, -v78
	v_fma_f32 v86, v80, s101, -v146
	v_fma_f32 v95, v84, s101, -v76
	v_fma_f32 v80, v81, s101, -v147
	v_fma_f32 v84, v87, s101, -v79
	v_fma_f32 v81, v82, s101, -v148
	v_fma_f32 v82, v83, s101, -v149
	v_max_f32_e32 v2, v3, v2
	v_max3_f32 v3, v92, v94, v88
	v_max3_f32 v83, v91, v85, v84
	v_max3_f32 v87, v86, v80, v81
	s_nop 0
	v_max3_f32 v76, v89, v90, v95
	v_max3_f32 v2, v2, v93, v3
	v_max3_f32 v3, v83, v87, v82
	v_max3_f32 v2, v2, v76, v3
	v_mov_b32_e32 v3, v2
	s_nop 1
	v_permlane16_swap_b32_e32 v2, v3
	v_max_f32_e32 v2, v2, v3
	v_mov_b32_e32 v3, v2
	s_nop 1
	v_permlane32_swap_b32_e32 v2, v3
	v_max_f32_e32 v124, v2, v3
	v_pk_add_f32 v[2:3], v[108:109], v[124:125]
	s_nop 0
	v_cmp_gt_f32_e32 vcc, v2, v3
	s_cbranch_vccz .LBB0_562
	v_max_f32_e32 v3, v109, v109
	v_max_f32_e32 v2, v3, v2
	v_sub_f32_e32 v3, v109, v2
	v_exp_f32_e32 v3, v3
	v_mov_b32_e32 v109, v2
	v_mul_f32_e32 v56, v56, v3
	v_mul_f32_e32 v57, v57, v3
	v_mul_f32_e32 v58, v58, v3
	v_mul_f32_e32 v59, v59, v3
	v_mul_f32_e32 v52, v52, v3
	v_mul_f32_e32 v53, v53, v3
	v_mul_f32_e32 v54, v54, v3
	v_mul_f32_e32 v55, v55, v3
	v_mul_f32_e32 v48, v48, v3
	v_mul_f32_e32 v49, v49, v3
	v_mul_f32_e32 v50, v50, v3
	v_mul_f32_e32 v51, v51, v3
	v_mul_f32_e32 v44, v44, v3
	v_mul_f32_e32 v45, v45, v3
	v_mul_f32_e32 v46, v46, v3
	v_mul_f32_e32 v47, v47, v3
	v_mul_f32_e32 v24, v24, v3
	v_mul_f32_e32 v25, v25, v3
	v_mul_f32_e32 v26, v26, v3
	v_mul_f32_e32 v27, v27, v3

; DEVI float opq(float x) { asm("" : "+v"(x)); return x; }
; DEVI float fexp2(float x) { return __builtin_amdgcn_exp2f(x); }
; template <int DK, int MODE, int RBM, class SF, class FF, class POST>
; DEVI void attn_tile_body(const bf16x8 (&qf)[2][DK / 32], const char* Ks, const char* Vs, SF& sf, FF& ff, POST& post,
;                          int cur, int c0, int c1, float (&m)[2], float (&l)[2], f32x4 (&o)[5][2], int fr, int fq) {
;     ...
;     if (cm == 2) {
;       const float cl = ff.cl(rb, cur);
;       const float fsc = ff.sc;
;       if (FF::HASVEC) {
; #pragma unroll
;         for (int kb = 0; kb < 4; ++kb) {
;           const f32x4 av = ff.vec(kb);
; #pragma unroll
;           for (int j = 0; j < 4; ++j) s[kb][rb][j] = opq(fmaf(s[kb][rb][j], fsc, av[j]));
;         }
;       }
;       if (MODE == 2) {
;         const float c = cl - m[rb];
; #pragma unroll
;         for (int kb = 0; kb < 4; ++kb)
; #pragma unroll
;           for (int j = 0; j < 4; ++j) {
;             const float e = FF::HASVEC ? opq(s[kb][rb][j] + c) : opq(fmaf(s[kb][rb][j], fsc, c));
;             s[kb][rb][j] = opq(fexp2(e) * l[rb]);
;           }
;       } else if (MODE == 0) {
;         float mx = max16(s[0][rb], s[1][rb], s[2][rb], s[3][rb]);
;         mx = xmax16(mx); mx = xmax32(mx);
;         const float cand = FF::HASVEC ? (mx + cl) : fmaf(mx, fsc, cl);
;         if (__builtin_amdgcn_ballot_w64(cand > m[rb] + DEFER_THR) != 0) {
;           const float mn = fmaxf(m[rb], cand);
;           const float alpha = fexp2(m[rb] - mn);
;           m[rb] = mn;
; #pragma unroll
;           for (int db = 0; db < 5; ++db)
; #pragma unroll
;             for (int j = 0; j < 4; ++j) o[db][rb][j] = opq(o[db][rb][j] * alpha);
;         }
.LBB0_567:
	s_or_b64 exec, exec, s[94:95]
	v_or_b32_e32 v80, 47, v196
	v_cmp_le_i32_e32 vcc, v80, v113
	s_and_saveexec_b64 s[82:83], vcc
	s_xor_b64 s[94:95], exec, s[82:83]
	s_cbranch_execz .LBB0_571
	ds_read_b128 v[78:81], v143 offset:33024
	s_waitcnt lgkmcnt(0)
	v_fma_f32 v78, v72, s101, -v78
	v_fma_f32 v77, v73, s101, -v79
	v_fma_f32 v73, v74, s101, -v80
	v_fma_f32 v72, v75, s101, -v81
	ds_read_b128 v[80:83], v143 offset:33088
	s_waitcnt lgkmcnt(0)
	v_fma_f32 v74, v68, s101, -v80
	v_fma_f32 v68, v69, s101, -v81
	v_fma_f32 v69, v70, s101, -v82
	v_fma_f32 v70, v71, s101, -v83
	ds_read_b128 v[80:83], v143 offset:33152
	v_max_f32_e32 v2, v77, v77
	v_max_f32_e32 v3, v78, v78
	s_waitcnt lgkmcnt(0)
	v_fma_f32 v75, v64, s101, -v80
	v_fma_f32 v71, v65, s101, -v81
	v_fma_f32 v65, v66, s101, -v82
	v_fma_f32 v64, v67, s101, -v83
	ds_read_b128 v[80:83], v143 offset:33216
	s_waitcnt lgkmcnt(0)
	v_fma_f32 v66, v60, s101, -v80
	v_fma_f32 v60, v61, s101, -v81
	v_fma_f32 v61, v62, s101, -v82
	v_fma_f32 v62, v63, s101, -v83
	v_max_f32_e32 v2, v3, v2
	v_max3_f32 v3, v72, v74, v68
	v_max3_f32 v67, v71, v65, v64
	v_max3_f32 v79, v66, v60, v61
	s_nop 0
	v_max3_f32 v63, v69, v70, v75
	v_max3_f32 v2, v2, v73, v3
	v_max3_f32 v3, v67, v79, v62
	v_max3_f32 v2, v2, v63, v3
	v_mov_b32_e32 v3, v2
	s_nop 1
	v_permlane16_swap_b32_e32 v2, v3
	v_max_f32_e32 v2, v2, v3
	v_mov_b32_e32 v3, v2
	s_nop 1
	v_permlane32_swap_b32_e32 v2, v3
	v_max_f32_e32 v124, v2, v3
	v_pk_add_f32 v[2:3], v[110:111], v[124:125]
	s_nop 0
	v_cmp_gt_f32_e32 vcc, v2, v3
	s_cbranch_vccz .LBB0_570
	v_max_f32_e32 v3, v111, v111
	v_max_f32_e32 v2, v3, v2
	v_sub_f32_e32 v3, v111, v2
	v_exp_f32_e32 v3, v3
	v_mov_b32_e32 v111, v2
	v_mul_f32_e32 v40, v40, v3
	v_mul_f32_e32 v41, v41, v3
	v_mul_f32_e32 v42, v42, v3
	v_mul_f32_e32 v43, v43, v3
	v_mul_f32_e32 v36, v36, v3
	v_mul_f32_e32 v37, v37, v3
	v_mul_f32_e32 v38, v38, v3
	v_mul_f32_e32 v39, v39, v3
	v_mul_f32_e32 v32, v32, v3
	v_mul_f32_e32 v33, v33, v3
	v_mul_f32_e32 v34, v34, v3
	v_mul_f32_e32 v35, v35, v3
	v_mul_f32_e32 v28, v28, v3
	v_mul_f32_e32 v29, v29, v3
	v_mul_f32_e32 v30, v30, v3
	v_mul_f32_e32 v31, v31, v3
	v_mul_f32_e32 v20, v20, v3
	v_mul_f32_e32 v21, v21, v3
	v_mul_f32_e32 v22, v22, v3
	v_mul_f32_e32 v23, v23, v3

; DEVI float opq(float x) { asm("" : "+v"(x)); return x; }
; template <int DK, int MODE, int RBM, class SF, class FF, class POST>
; DEVI void attn_tile_body(const bf16x8 (&qf)[2][DK / 32], const char* Ks, const char* Vs, SF& sf, FF& ff, POST& post,
;                          int cur, int c0, int c1, float (&m)[2], float (&l)[2], f32x4 (&o)[5][2], int fr, int fq) {
;     ...
;   for (int ks = 0; ks < NKC; ++ks)
; #pragma unroll
;     for (int kb = 0; kb < 4; ++kb) {
;       const int koff = DK == 64 ? (kb * 16 + fr) * 128 + (((ks * 4 + fq) ^ (fr & 7)) * 16)
;                                 : (kb * 16 + fr) * 192 + ((ks * 4 + (fq ^ ((fr >> 2) & 3))) * 16);
;       bf16x8 kf = *(const bf16x8*)(Ks + koff);
;       if (RBM & 1) s[kb][0] = __builtin_amdgcn_mfma_f32_16x16x32_bf16(kf, qf[0][ks], s[kb][0], 0, 0, 0);
;       if (RBM & 2) s[kb][1] = __builtin_amdgcn_mfma_f32_16x16x32_bf16(kf, qf[1][ks], s[kb][1], 0, 0, 0);
;     }
; #pragma unroll
;   for (int rb = 0; rb < 2; ++rb) {
;     if (!(RBM & (1 << rb))) continue;
;     const int cm = rb == 0 ? c0 : c1;
;     if (cm == 2) {
;       const float cl = ff.cl(rb, cur);
;       const float fsc = ff.sc;
;       if (FF::HASVEC) {
; #pragma unroll
;         for (int kb = 0; kb < 4; ++kb) {
;           const f32x4 av = ff.vec(kb);
; #pragma unroll
;           for (int j = 0; j < 4; ++j) s[kb][rb][j] = opq(fmaf(s[kb][rb][j], fsc, av[j]));
;         }
;       }
;       if (MODE == 2) {
;         const float c = cl - m[rb];
; #pragma unroll
;         for (int kb = 0; kb < 4; ++kb)
; #pragma unroll
;           for (int j = 0; j < 4; ++j) {
;             const float e = FF::HASVEC ? opq(s[kb][rb][j] + c) : opq(fmaf(s[kb][rb][j], fsc, c));
;             s[kb][rb][j] = opq(fexp2(e) * l[rb]);
;           }
;       } else if (MODE == 0) {
;         float mx = max16(s[0][rb], s[1][rb], s[2][rb], s[3][rb]);
;         mx = xmax16(mx); mx = xmax32(mx);
;         const float cand = FF::HASVEC ? (mx + cl) : fmaf(mx, fsc, cl);
;         if (__builtin_amdgcn_ballot_w64(cand > m[rb] + DEFER_THR) != 0) {
;           const float mn = fmaxf(m[rb], cand);
;           const float alpha = fexp2(m[rb] - mn);
;           m[rb] = mn;
; #pragma unroll
;           for (int db = 0; db < 5; ++db)
; #pragma unroll
;             for (int j = 0; j < 4; ++j) o[db][rb][j] = opq(o[db][rb][j] * alpha);
;         }
.LBB0_592:
	s_or_b64 exec, exec, s[42:43]
	v_lshrrev_b64 v[68:69], v66, v[112:113]
	v_and_b32_e32 v0, 1, v68
	v_cmp_eq_u32_e32 vcc, 1, v0
	s_and_saveexec_b64 s[52:53], vcc
	s_cbranch_execz .LBB0_585
	v_lshlrev_b32_e32 v195, 6, v66
	v_or_b32_e32 v0, 63, v195
	v_cmp_le_i32_e32 vcc, v0, v137
	v_or_b32_e32 v0, s6, v129
	v_add_u32_e32 v0, v0, v130
	ds_read_b128 v[66:69], v0
	ds_read_b128 v[144:147], v0 offset:64
	ds_read_b128 v[74:77], v0 offset:3072
	ds_read_b128 v[82:85], v0 offset:6144
	ds_read_b128 v[90:93], v0 offset:9216
	v_add_f32_e32 v207, 0x41000000, v141
	s_waitcnt lgkmcnt(0)
	v_mfma_f32_16x16x32_bf16 v[70:73], v[66:69], v[18:21], 0
	v_mfma_f32_16x16x32_bf16 v[66:69], v[66:69], v[10:13], 0
	v_mfma_f32_16x16x32_bf16 v[70:73], v[144:147], v[2:5], v[70:73]
	v_mfma_f32_16x16x32_bf16 v[66:69], v[144:147], v[14:17], v[66:69]
	ds_read_b128 v[144:147], v0 offset:3136
	v_mfma_f32_16x16x32_bf16 v[78:81], v[74:77], v[18:21], 0
	s_waitcnt lgkmcnt(0)
	v_mfma_f32_16x16x32_bf16 v[148:151], v[144:147], v[2:5], v[78:81]
	s_nop 5
	ds_read_b128 v[78:81], v0 offset:6208
	v_mfma_f32_16x16x32_bf16 v[74:77], v[74:77], v[10:13], 0
	v_mfma_f32_16x16x32_bf16 v[86:89], v[82:85], v[18:21], 0
	v_mfma_f32_16x16x32_bf16 v[82:85], v[82:85], v[10:13], 0
	v_mfma_f32_16x16x32_bf16 v[74:77], v[144:147], v[14:17], v[74:77]
	s_waitcnt lgkmcnt(0)
	v_mfma_f32_16x16x32_bf16 v[86:89], v[78:81], v[2:5], v[86:89]
	v_mfma_f32_16x16x32_bf16 v[144:147], v[78:81], v[14:17], v[82:85]
	ds_read_b128 v[78:81], v0 offset:9280
	v_mfma_f32_16x16x32_bf16 v[94:97], v[90:93], v[18:21], 0
	v_mfma_f32_16x16x32_bf16 v[90:93], v[90:93], v[10:13], 0
	s_waitcnt lgkmcnt(0)
	v_mfma_f32_16x16x32_bf16 v[196:199], v[78:81], v[2:5], v[94:97]
	v_mfma_f32_16x16x32_bf16 v[200:203], v[78:81], v[14:17], v[90:93]
	ds_read_b128 v[78:81], v0 offset:128
	s_waitcnt lgkmcnt(0)
	v_mfma_f32_16x16x32_bf16 v[94:97], v[78:81], v[6:9], v[70:73]
	s_nop 2
	ds_read_b128 v[70:73], v0 offset:6272
	v_mfma_f32_16x16x32_bf16 v[78:81], v[78:81], v[22:25], v[66:69]
	s_nop 2
	ds_read_b128 v[66:69], v0 offset:3200
	s_waitcnt lgkmcnt(0)
	v_mfma_f32_16x16x32_bf16 v[82:85], v[66:69], v[6:9], v[148:151]
	v_mfma_f32_16x16x32_bf16 v[66:69], v[66:69], v[22:25], v[74:77]
	s_nop 2
	ds_read_b128 v[74:77], v0 offset:9344
	v_mfma_f32_16x16x32_bf16 v[86:89], v[70:73], v[6:9], v[86:89]
	v_mfma_f32_16x16x32_bf16 v[70:73], v[70:73], v[22:25], v[144:147]
	s_waitcnt lgkmcnt(0)
	v_mfma_f32_16x16x32_bf16 v[90:93], v[74:77], v[6:9], v[196:199]
	v_mfma_f32_16x16x32_bf16 v[74:77], v[74:77], v[22:25], v[200:203]
	s_and_saveexec_b64 s[42:43], vcc
	s_xor_b64 s[54:55], exec, s[42:43]
	s_cbranch_execz .LBB0_597
	v_max_f32_e32 v0, v94, v95
	v_max3_f32 v143, v97, v82, v83
	v_max3_f32 v145, v87, v88, v89
	s_nop 0
	v_max3_f32 v146, v90, v91, v92
	v_max3_f32 v144, v84, v85, v86
	v_max3_f32 v0, v0, v96, v143
	v_max3_f32 v143, v145, v146, v93
	v_max3_f32 v0, v0, v144, v143
	v_mov_b32_e32 v143, v0
	s_nop 1
	v_permlane16_swap_b32_e32 v0, v143
	v_max_f32_e32 v0, v0, v143
	v_mov_b32_e32 v143, v0
	s_nop 1
	v_permlane32_swap_b32_e32 v0, v143
	v_max_f32_e32 v0, v0, v143
	s_mov_b32 s7, 0x3e16c740
	v_fma_f32 v0, v0, s7, 0
	v_cmp_gt_f32_e32 vcc, v0, v207
	s_cbranch_vccz .LBB0_596
	v_max_f32_e32 v143, v141, v141
	v_max_f32_e32 v0, v143, v0
	v_sub_f32_e32 v141, v141, v0
	v_exp_f32_e32 v141, v141
	s_nop 0
	v_mul_f32_e32 v62, v62, v141
	v_mul_f32_e32 v63, v63, v141
	v_mul_f32_e32 v64, v64, v141
	v_mul_f32_e32 v65, v65, v141
	v_mul_f32_e32 v58, v58, v141
	v_mul_f32_e32 v59, v59, v141
	v_mul_f32_e32 v60, v60, v141
	v_mul_f32_e32 v61, v61, v141
	v_mul_f32_e32 v54, v54, v141
	v_mul_f32_e32 v55, v55, v141
	v_mul_f32_e32 v56, v56, v141
	v_mul_f32_e32 v57, v57, v141
	v_mul_f32_e32 v50, v50, v141
	v_mul_f32_e32 v51, v51, v141
	v_mul_f32_e32 v52, v52, v141
	v_mul_f32_e32 v53, v53, v141
	v_mul_f32_e32 v42, v42, v141
	v_mul_f32_e32 v43, v43, v141
	v_mul_f32_e32 v44, v44, v141
	v_mul_f32_e32 v45, v45, v141
	v_mov_b32_e32 v141, v0

; __global__ void __launch_bounds__(256, 2) mega(Params p) {
;   __shared__ __attribute__((aligned(16))) char smem[SMEM_BYTES];
	.amdhsa_kernel _Z4mega6Params
		.amdhsa_group_segment_fixed_size 77232
		.amdhsa_private_segment_fixed_size 0
		.amdhsa_kernarg_size 464
		.amdhsa_user_sgpr_count 2
		.amdhsa_user_sgpr_dispatch_ptr 0
		.amdhsa_user_sgpr_queue_ptr 0
		.amdhsa_user_sgpr_kernarg_segment_ptr 1
		.amdhsa_user_sgpr_dispatch_id 0
		.amdhsa_user_sgpr_kernarg_preload_length 0
		.amdhsa_user_sgpr_kernarg_preload_offset 0
		.amdhsa_user_sgpr_private_segment_size 0
		.amdhsa_uses_dynamic_stack 0
		.amdhsa_enable_private_segment 0
		.amdhsa_system_sgpr_workgroup_id_x 1
		.amdhsa_system_sgpr_workgroup_id_y 0
		.amdhsa_system_sgpr_workgroup_id_z 0
		.amdhsa_system_sgpr_workgroup_info 0
		.amdhsa_system_vgpr_workitem_id 2
		.amdhsa_next_free_vgpr 252
		.amdhsa_next_free_sgpr 102
		.amdhsa_accum_offset 252
		.amdhsa_reserve_vcc 1
		.amdhsa_float_round_mode_32 0
		.amdhsa_float_round_mode_16_64 0
		.amdhsa_float_denorm_mode_32 3
		.amdhsa_float_denorm_mode_16_64 3
		.amdhsa_dx10_clamp 1
		.amdhsa_ieee_mode 1
		.amdhsa_fp16_overflow 0
		.amdhsa_tg_split 0
		.amdhsa_exception_fp_ieee_invalid_op 0
		.amdhsa_exception_fp_denorm_src 0
		.amdhsa_exception_fp_ieee_div_zero 0
		.amdhsa_exception_fp_ieee_overflow 0
		.amdhsa_exception_fp_ieee_underflow 0
		.amdhsa_exception_fp_ieee_inexact 0
		.amdhsa_exception_int_div_zero 0
	.end_amdhsa_kernel

; __global__ void __launch_bounds__(256, 2) mega(Params p) {
;   __shared__ __attribute__((aligned(16))) char smem[SMEM_BYTES];
amdhsa.kernels:
  - .agpr_count:     0
    .args:
      - .offset:         0
        .size:           208
        .value_kind:     by_value
      - .offset:         208
        .size:           4
        .value_kind:     hidden_block_count_x
      - .offset:         212
        .size:           4
        .value_kind:     hidden_block_count_y
      - .offset:         216
        .size:           4
        .value_kind:     hidden_block_count_z
      - .offset:         220
        .size:           2
        .value_kind:     hidden_group_size_x
      - .offset:         222
        .size:           2
        .value_kind:     hidden_group_size_y
      - .offset:         224
        .size:           2
        .value_kind:     hidden_group_size_z
      - .offset:         226
        .size:           2
        .value_kind:     hidden_remainder_x
      - .offset:         228
        .size:           2
        .value_kind:     hidden_remainder_y
      - .offset:         230
        .size:           2
        .value_kind:     hidden_remainder_z
      - .offset:         248
        .size:           8
        .value_kind:     hidden_global_offset_x
      - .offset:         256
        .size:           8
        .value_kind:     hidden_global_offset_y
      - .offset:         264
        .size:           8
        .value_kind:     hidden_global_offset_z
      - .offset:         272
        .size:           2
        .value_kind:     hidden_grid_dims
      - .offset:         296
        .size:           8
        .value_kind:     hidden_multigrid_sync_arg
    .group_segment_fixed_size: 77232
    .kernarg_segment_align: 8
    .kernarg_segment_size: 464
    .language:       OpenCL C
    .language_version:
      - 2
      - 0
    .max_flat_workgroup_size: 256
    .name:           _Z4mega6Params
    .private_segment_fixed_size: 0
    .sgpr_count:     108
    .sgpr_spill_count: 222
    .symbol:         _Z4mega6Params.kd
    .uniform_work_group_size: 1
    .uses_dynamic_stack: false
    .vgpr_count:     252
    .vgpr_spill_count: 0
    .wavefront_size: 64
